# v033 + static s_setprio 1 for waves 4-7 during the attention phase as well (reset at its exit)
# baseline (speedup 1.0000x reference)
.LBB0_26:
	v_readlane_b32 s0, v254, 47
	s_cmp_eq_u32 s0, 0
	s_cselect_b64 s[10:11], -1, 0
	v_writelane_b32 v254, s10, 50
	s_cmp_lg_u32 s0, 0
	s_mov_b64 s[0:1], -1
	v_writelane_b32 v254, s11, 51
	s_cbranch_scc0 .LBB0_367
	v_readlane_b32 s0, v254, 47
	s_add_i32 s0, s0, -1
	s_mul_hi_i32 s1, s0, 0x2aaaaaab
	s_lshr_b32 s10, s1, 31
	s_add_i32 s30, s1, s10
	s_mov_b32 s10, s30
	v_writelane_b32 v254, s10, 52
	s_mul_i32 s1, s30, 6
	s_sub_i32 s67, s0, s1
	v_writelane_b32 v254, s11, 53
	s_mov_b64 s[40:41], -1
	v_readlane_b32 s0, v254, 48
	v_readlane_b32 s1, v254, 49
	s_and_b64 s[0:1], s[0:1], exec
	v_readlane_b32 s0, v252, 12
	v_readlane_b32 s1, v252, 31
	s_cselect_b32 s22, s0, s1
	s_mov_b64 s[70:71], 0
	s_cmp_lt_i32 s67, 1
	s_mov_b64 s[38:39], 0
	s_cbranch_scc1 .LBB0_45
	s_cmp_eq_u32 s67, 1
	s_mov_b64 s[38:39], -1
	s_cbranch_scc0 .LBB0_104
	s_lshl_b32 s0, s22, 5
	s_add_i32 s8, s58, s0
	s_ashr_i32 s52, s8, 5
	s_ashr_i32 s53, s52, 31
	s_mul_i32 s1, s52, 0x1c00000
	s_mul_hi_i32 s0, s52, 0x1c00000
	s_add_u32 s68, s54, s1
	v_writelane_b32 v254, s1, 60
	s_mov_b32 s9, s0
	s_addc_u32 s28, s55, s0
	s_lshl_b64 s[0:1], s[52:53], 22
	s_sub_u32 s0, 0, s0
	v_writelane_b32 v254, s0, 62
	s_subb_u32 s0, 0, s1
	v_writelane_b32 v254, s0, 54
	s_lshl_b64 s[0:1], s[52:53], 13
	s_sub_u32 s0, 0, s0
	v_writelane_b32 v254, s0, 55
	s_subb_u32 s0, 0, s1
	v_writelane_b32 v254, s0, 58
	s_lshl_b64 s[0:1], s[52:53], 23
	s_mov_b32 s69, s49
	s_sub_u32 s49, 0, s0
	s_subb_u32 s0, 0, s1
	v_writelane_b32 v254, s0, 61
	s_mov_b32 s66, s58
	v_readlane_b32 s0, v254, 19
	s_cmpk_gt_i32 s8, 0xff
	s_nop 0
	v_mov_b32_e32 v0, s0
	ds_read_b32 v0, v0
	s_waitcnt lgkmcnt(0)
	v_readfirstlane_b32 s0, v0
	s_nop 1
	v_writelane_b32 v254, s0, 57
	s_nop 0
	v_readlane_b32 s0, v254, 20
	s_nop 1
	v_mov_b32_e32 v0, s0
	ds_read_b32 v0, v0
	s_waitcnt lgkmcnt(0)
	v_readfirstlane_b32 s0, v0
	s_nop 1
	v_writelane_b32 v255, s0, 0
	v_readlane_b32 s0, v254, 18
	s_nop 1
	v_mov_b32_e32 v0, s0
	ds_read_b32 v0, v0
	s_waitcnt lgkmcnt(0)
	v_readfirstlane_b32 s0, v0
	s_nop 1
	v_writelane_b32 v255, s0, 1
	v_readlane_b32 s0, v254, 17
	s_nop 1
	v_mov_b32_e32 v0, s0
	ds_read_b32 v0, v0
	s_waitcnt lgkmcnt(0)
	s_barrier
	v_readfirstlane_b32 s0, v0
	s_nop 1
	v_writelane_b32 v255, s0, 2
	s_cbranch_scc1 .LBB0_48
	v_readlane_b32 s0, v254, 62
	s_add_u32 s0, s68, s0
	v_readlane_b32 s1, v254, 54
	s_addc_u32 s1, s28, s1
	s_add_u32 s34, s0, 0x4400000
	s_addc_u32 s37, s1, 0
	s_add_u32 s94, s0, 0x4800000
	s_addc_u32 s31, s1, 0
	v_readlane_b32 s0, v254, 55
	s_add_u32 s0, s68, s0
	v_readlane_b32 s1, v254, 58
	s_addc_u32 s1, s28, s1
	s_add_u32 s95, s0, 0x5000000
	s_addc_u32 s35, s1, 0
	s_add_u32 s38, s68, s49
	v_readlane_b32 s0, v254, 61
	s_addc_u32 s39, s28, s0
	v_readlane_b32 s0, v254, 52
	s_mov_b32 s10, s0
	s_add_i32 s0, s0, 1
	v_readlane_b32 s1, v254, 53
	v_cvt_f32_i32_e32 v0, s0
	s_lshl_b32 s0, s10, 7
	s_ashr_i32 s1, s0, 31
	v_readlane_b32 s72, v252, 15
	s_lshl_b64 s[0:1], s[0:1], 2
	v_readlane_b32 s82, v252, 25
	v_readlane_b32 s83, v252, 26
	s_add_u32 s40, s82, s0
	s_addc_u32 s41, s83, s1
	s_lshl_b32 s0, s10, 6
	s_ashr_i32 s1, s0, 31
	v_readlane_b32 s74, v252, 17
	s_lshl_b64 s[0:1], s[0:1], 2
	v_mul_f32_e32 v0, 0xbe99999a, v0
	v_readlane_b32 s75, v252, 18
	s_add_u32 s42, s74, s0
	v_mul_f32_e32 v1, 0x3fb8aa3b, v0
	v_readlane_b32 s76, v252, 19
	s_addc_u32 s43, s75, s1
	v_fma_f32 v2, v0, s23, -v1
	v_rndne_f32_e32 v3, v1
	v_readlane_b32 s77, v252, 20
	s_add_u32 s44, s76, s0
	v_fmac_f32_e32 v2, 0x32a5705f, v0
	v_sub_f32_e32 v1, v1, v3
	v_readlane_b32 s78, v252, 21
	s_addc_u32 s45, s77, s1
	v_add_f32_e32 v1, v1, v2
	v_readlane_b32 s79, v252, 22
	s_add_u32 s46, s78, s0
	v_cvt_i32_f32_e32 v2, v3
	v_exp_f32_e32 v1, v1
	v_readlane_b32 s80, v252, 23
	s_addc_u32 s47, s79, s1
	v_readlane_b32 s81, v252, 24
	s_add_u32 s50, s80, s0
	s_addc_u32 s51, s81, s1
	s_mul_i32 s1, s52, 0x1800000
	s_mul_hi_i32 s0, s52, 0x1800000
	s_add_u32 s36, s1, 0x4820000
	v_ldexp_f32 v1, v1, v2
	v_cmp_ngt_f32_e32 vcc, s17, v0
	s_addc_u32 s29, s0, 0
	s_lshl_b32 s0, s22, 12
	s_lshl_b32 s1, s66, 7
	v_cndmask_b32_e32 v1, 0, v1, vcc
	v_cmp_nlt_f32_e32 vcc, s21, v0
	s_add_i32 s30, s0, s1
	s_lshl_b32 s0, s22, 10
	s_lshl_b32 s1, s66, 5
	v_cndmask_b32_e32 v0, v213, v1, vcc
	s_add_i32 s25, s0, s1
	s_mul_i32 s0, s52, 0x1bfe000
	v_fmamk_f32 v194, v0, 0xbf19999a, v209
	s_mul_hi_i32 s1, s52, 0x1bfe000
	s_add_u32 s0, s0, 0x5000100
	v_sub_f32_e32 v195, 1.0, v194
	s_addc_u32 s1, s1, 0
	s_mov_b32 s10, s8
	v_readlane_b32 s73, v252, 16
	v_readlane_b32 s84, v252, 27
	v_readlane_b32 s85, v252, 28
	v_readlane_b32 s86, v252, 29
	v_readlane_b32 s87, v252, 30
	v_readfirstlane_b32 s101, v208
	s_nop 3
	s_lshr_b32 s101, s101, 8
	s_cmp_eq_u32 s101, 0
	s_cbranch_scc1 .Lprio_b_done
	s_setprio 1
.Lprio_b_done:
	s_branch .LBB0_32
.LBB0_31:
	v_readlane_b32 s11, v254, 1
	s_add_i32 s30, s30, s11
	v_readlane_b32 s11, v254, 2
	s_add_i32 s10, s10, s4
	s_add_i32 s25, s25, s11
	s_cmpk_gt_i32 s10, 0xff
	s_cbranch_scc1 .LBB0_48

.LBB0_48:
	s_setprio 0
	v_mov_b64_e32 v[174:175], 0
	v_mov_b64_e32 v[178:179], 0xb00
	v_mov_b64_e32 v[180:181], 0x200
	v_mov_b64_e32 v[182:183], 0x1ff
	v_mov_b64_e32 v[184:185], 0x2ff
	v_mov_b64_e32 v[186:187], 0x300
	s_barrier
	s_mov_b64 s[38:39], exec
	v_readlane_b32 s0, v252, 13
	v_readlane_b32 s1, v252, 14
	s_and_b64 s[0:1], s[38:39], s[0:1]
	s_mov_b64 exec, s[0:1]
	s_cbranch_execz .LBB0_50
	v_readlane_b32 s0, v254, 19
	s_nop 1
	v_mov_b32_e32 v0, s0
	v_readlane_b32 s0, v254, 57
	s_nop 1
	v_mov_b32_e32 v1, s0
	v_readlane_b32 s0, v254, 20
	ds_write_b32 v0, v1
	s_nop 0
	v_mov_b32_e32 v0, s0
	v_readlane_b32 s0, v255, 0
	s_nop 1
	v_mov_b32_e32 v1, s0
	v_readlane_b32 s0, v254, 18
	ds_write_b32 v0, v1
	s_nop 0
	v_mov_b32_e32 v0, s0
	v_readlane_b32 s0, v255, 1
	s_nop 1
	v_mov_b32_e32 v1, s0
	v_readlane_b32 s0, v254, 17
	ds_write_b32 v0, v1
	s_nop 0
	v_mov_b32_e32 v0, s0
	v_readlane_b32 s0, v255, 2
	s_nop 1
	v_mov_b32_e32 v1, s0
	ds_write_b32 v0, v1
